# attention work queue: next item's dequeue issued at the start of the item epilogue (its round trip overlaps the epilogue)
# baseline (speedup 1.0000x reference)
.LBB0_855:
	s_or_b64 exec, exec, s[44:45]
	ds_bpermute_b32 v64, v115, v131
	s_and_b64 s[10:11], s[2:3], s[8:9]
	s_waitcnt vmcnt(0) lgkmcnt(0)
	s_barrier
	s_mov_b64 s[62:63], exec
	v_readlane_b32 s64, v254, 11
	v_readlane_b32 s65, v254, 12
	s_and_b64 s[64:65], s[62:63], s[64:65]
	s_mov_b64 exec, s[64:65]
	s_cbranch_execz .Lpf_a
	v_mov_b32_e32 v219, v113
	v_mov_b32_e32 v218, v134
	v_lshl_add_u64 v[218:219], v[218:219], 2, s[18:19]
	global_atomic_add v216, v[218:219], v166, off sc0
.Lpf_a:
	s_mov_b64 exec, s[62:63]
	v_add_f32_e32 v64, v131, v64
	v_rcp_f32_e32 v64, v64
	s_nop 0
	v_cndmask_b32_e64 v64, 0, v64, s[8:9]
	s_and_saveexec_b64 s[0:1], s[10:11]
	s_cbranch_execz .LBB0_857
	v_mul_f32_e32 v65, v164, v64
	v_mul_f32_e32 v66, v48, v65
	v_mul_f32_e32 v67, v49, v65
	ds_write2st64_b32 v154, v66, v67 offset1:1
	v_mul_f32_e32 v66, v50, v65
	v_mul_f32_e32 v67, v51, v65
	ds_write2st64_b32 v154, v66, v67 offset0:2 offset1:3
	v_mul_f32_e32 v66, v52, v65
	v_mul_f32_e32 v67, v53, v65
	ds_write2st64_b32 v154, v66, v67 offset0:4 offset1:5
	v_mul_f32_e32 v66, v54, v65
	v_mul_f32_e32 v67, v55, v65
	ds_write2st64_b32 v154, v66, v67 offset0:6 offset1:7
	v_mul_f32_e32 v66, v56, v65
	v_mul_f32_e32 v67, v57, v65
	ds_write2st64_b32 v154, v66, v67 offset0:8 offset1:9
	v_mul_f32_e32 v66, v58, v65
	v_mul_f32_e32 v67, v59, v65
	ds_write2st64_b32 v154, v66, v67 offset0:10 offset1:11
	v_mul_f32_e32 v66, v60, v65
	v_mul_f32_e32 v67, v61, v65
	ds_write2st64_b32 v154, v66, v67 offset0:12 offset1:13
	v_mul_f32_e32 v66, v62, v65
	v_mul_f32_e32 v67, v63, v65
	ds_write2st64_b32 v154, v66, v67 offset0:14 offset1:15
	v_mul_f32_e32 v66, v32, v65
	v_mul_f32_e32 v67, v33, v65
	ds_write2st64_b32 v154, v66, v67 offset0:16 offset1:17
	v_mul_f32_e32 v66, v34, v65
	v_mul_f32_e32 v67, v35, v65
	ds_write2st64_b32 v154, v66, v67 offset0:18 offset1:19
	v_mul_f32_e32 v66, v36, v65
	v_mul_f32_e32 v67, v37, v65
	ds_write2st64_b32 v154, v66, v67 offset0:20 offset1:21
	v_mul_f32_e32 v66, v38, v65
	v_mul_f32_e32 v67, v39, v65
	ds_write2st64_b32 v154, v66, v67 offset0:22 offset1:23
	v_mul_f32_e32 v66, v40, v65
	v_mul_f32_e32 v67, v41, v65
	ds_write2st64_b32 v154, v66, v67 offset0:24 offset1:25
	v_mul_f32_e32 v66, v42, v65
	v_mul_f32_e32 v67, v43, v65
	ds_write2st64_b32 v154, v66, v67 offset0:26 offset1:27
	v_mul_f32_e32 v66, v44, v65
	v_mul_f32_e32 v67, v45, v65
	ds_write2st64_b32 v154, v66, v67 offset0:28 offset1:29
	v_mul_f32_e32 v66, v46, v65
	v_mul_f32_e32 v67, v47, v65
	ds_write2st64_b32 v154, v66, v67 offset0:30 offset1:31
	v_mul_f32_e32 v66, v16, v65
	v_mul_f32_e32 v67, v17, v65
	ds_write2st64_b32 v154, v66, v67 offset0:32 offset1:33
	v_mul_f32_e32 v66, v18, v65
	v_mul_f32_e32 v67, v19, v65
	ds_write2st64_b32 v154, v66, v67 offset0:34 offset1:35
	v_mul_f32_e32 v66, v20, v65
	v_mul_f32_e32 v67, v21, v65
	ds_write2st64_b32 v154, v66, v67 offset0:36 offset1:37
	v_mul_f32_e32 v66, v22, v65
	v_mul_f32_e32 v67, v23, v65
	ds_write2st64_b32 v154, v66, v67 offset0:38 offset1:39
	v_mul_f32_e32 v66, v24, v65
	v_mul_f32_e32 v67, v25, v65
	ds_write2st64_b32 v154, v66, v67 offset0:40 offset1:41
	v_mul_f32_e32 v66, v26, v65
	v_mul_f32_e32 v67, v27, v65
	ds_write2st64_b32 v154, v66, v67 offset0:42 offset1:43
	v_mul_f32_e32 v66, v28, v65
	v_mul_f32_e32 v67, v29, v65
	ds_write2st64_b32 v154, v66, v67 offset0:44 offset1:45
	v_mul_f32_e32 v66, v30, v65
	v_mul_f32_e32 v67, v31, v65
	ds_write2st64_b32 v154, v66, v67 offset0:46 offset1:47
	v_mul_f32_e32 v66, v0, v65
	v_mul_f32_e32 v67, v1, v65
	ds_write2st64_b32 v154, v66, v67 offset0:48 offset1:49
	v_mul_f32_e32 v66, v2, v65
	v_mul_f32_e32 v67, v3, v65
	ds_write2st64_b32 v154, v66, v67 offset0:50 offset1:51
	v_mul_f32_e32 v66, v4, v65
	v_mul_f32_e32 v67, v5, v65
	ds_write2st64_b32 v154, v66, v67 offset0:52 offset1:53
	v_mul_f32_e32 v66, v6, v65
	v_mul_f32_e32 v67, v7, v65
	ds_write2st64_b32 v154, v66, v67 offset0:54 offset1:55
	v_mul_f32_e32 v66, v8, v65
	v_mul_f32_e32 v67, v9, v65
	ds_write2st64_b32 v154, v66, v67 offset0:56 offset1:57
	v_mul_f32_e32 v66, v10, v65
	v_mul_f32_e32 v67, v11, v65
	ds_write2st64_b32 v154, v66, v67 offset0:58 offset1:59
	v_mul_f32_e32 v66, v12, v65
	v_mul_f32_e32 v67, v13, v65
	ds_write2st64_b32 v154, v66, v67 offset0:60 offset1:61
	v_mul_f32_e32 v66, v14, v65
	v_mul_f32_e32 v65, v15, v65
	ds_write2st64_b32 v154, v66, v65 offset0:62 offset1:63
